# prep items: the static priority raise given to waves 0-3 instead of 4-7 (A/B of which half)
# speedup vs baseline: 1.0049x; 1.0012x over previous
; DI unsigned xb_add(unsigned* p, unsigned v) { return __hip_atomic_fetch_add(p, v, __ATOMIC_RELAXED, __HIP_MEMORY_SCOPE_AGENT); }
; #define ITEM_BEGIN { size_t z_ = 0; asm volatile("" : "+s"(z_)); q.ws = p.ws + z_; sm = smem + osgpr(0); }
; __global__ __launch_bounds__(512, 2) void mega(P p) {
;     ...
;             if (threadIdx.x == 0) qw[0] = xb_add(qctr, 1u);
;             __syncthreads();
;             int it = (int)qw[0];
;             __syncthreads();
;             while (it < ntot) {
;                 ITEM_BEGIN
;                 if (threadIdx.x == 0) nxt = xb_add(qctr, 1u);
;                 if (it < 576) { for (int r2 = 0; r2 < REP_GDNP; ++r2) gdn_prep_item(q, l, it, sm); }
.LBB0_242:
	v_readfirstlane_b32 s98, v166
	s_nop 0
	s_lshr_b32 s98, s98, 6
	s_cmp_ge_u32 s98, 4
	s_cbranch_scc1 .Lprep_prio_done
	s_setprio 1
